# fnet-latent DFT as 64x64 Cooley-Tukey on MFMA (two stage, per-wave), tables built in phase 0
# speedup vs baseline: 1.1617x; 1.1617x over previous
.LBB0_672:
	s_andn2_b64 vcc, exec, s[0:1]
	s_cbranch_vccnz .LBB0_718
	s_barrier
	v_lshrrev_b32_e32 v0, 6, v151
	s_nop 0
	v_readfirstlane_b32 s14, v0
	s_add_i32 s0, s89, 0xfffffe00
	s_lshr_b32 s42, s0, 6
	s_and_b32 s48, s0, 63
	s_lshl_b32 s48, s48, 2
	s_lshl_b32 s42, s42, 12
	s_addk_i32 s42, 0x2000
	s_add_i32 s50, s48, s14
	s_mul_i32 s0, s50, 0xc000
	s_lshl_b32 s1, s42, 1
	s_add_u32 s0, s0, s1
	s_add_u32 s0, s0, 0xc000000
	s_add_u32 s4, s94, s0
	s_addc_u32 s5, s95, 0
	s_add_u32 s6, s4, 0xc00000
	s_addc_u32 s7, s5, 0
	s_add_u32 s8, s94, 0xfca0000
	s_addc_u32 s9, s95, 0
	s_add_u32 s28, s94, 0xfca8000
	s_addc_u32 s29, s95, 0
	s_mul_i32 s0, s42, 0x600
	s_lshl_b32 s1, s48, 1
	s_add_u32 s0, s0, s1
	s_add_u32 s0, s0, 0x4800400
	s_add_u32 s38, s94, s0
	s_addc_u32 s39, s95, 0
	s_lshl_b32 s0, s42, 11
	s_add_u32 s0, s0, s1
	s_addk_i32 s0, 0x600
	s_add_u32 s40, s94, s0
	s_addc_u32 s41, s95, 0
	v_readlane_b32 s0, v252, 7
	v_readlane_b32 s1, v252, 8
	s_lshl_b32 s52, s80, 8
	s_add_i32 s52, s52, s50
	s_lshl_b32 s52, s52, 2
	s_add_u32 s0, s0, s52
	s_addc_u32 s1, s1, 0
	s_load_dword s52, s[0:1], 0x0
	v_and_b32_e32 v0, 63, v151
	v_and_b32_e32 v138, 15, v0
	v_lshrrev_b32_e32 v139, 4, v0
	v_lshlrev_b32_e32 v168, 2, v139
	v_cvt_f32_u32_e32 v140, v168
	v_lshlrev_b32_e32 v145, 4, v0
	v_add_u32_e32 v156, 0x1000, v145
	v_add_u32_e32 v157, 0x2000, v145
	v_add_u32_e32 v158, 0x3000, v145
	v_add_u32_e32 v159, 0x4000, v145
	v_lshlrev_b32_e32 v160, 1, v138
	v_lshl_or_b32 v160, v139, 10, v160
	v_add_u32_e32 v161, 0x1000, v160
	v_lshlrev_b32_e32 v144, 3, v138
	v_lshl_or_b32 v144, v139, 11, v144
	s_lshl_b32 s0, s14, 1
	v_add_u32_e32 v144, s0, v144
	v_mov_b32_e32 v141, v138
	global_load_ushort v2, v160, s[4:5] offset:0
	global_load_ushort v3, v160, s[4:5] offset:256
	global_load_ushort v4, v160, s[4:5] offset:512
	global_load_ushort v5, v160, s[4:5] offset:768
	global_load_ushort v6, v161, s[4:5] offset:0
	global_load_ushort v7, v161, s[4:5] offset:256
	global_load_ushort v8, v161, s[4:5] offset:512
	global_load_ushort v9, v161, s[4:5] offset:768
	global_load_ushort v10, v160, s[6:7] offset:0
	global_load_ushort v11, v160, s[6:7] offset:256
	global_load_ushort v12, v160, s[6:7] offset:512
	global_load_ushort v13, v160, s[6:7] offset:768
	global_load_ushort v14, v161, s[6:7] offset:0
	global_load_ushort v15, v161, s[6:7] offset:256
	global_load_ushort v16, v161, s[6:7] offset:512
	global_load_ushort v17, v161, s[6:7] offset:768
	global_load_ushort v66, v160, s[4:5] offset:128
	global_load_ushort v67, v160, s[4:5] offset:384
	global_load_ushort v68, v160, s[4:5] offset:640
	global_load_ushort v69, v160, s[4:5] offset:896
	global_load_ushort v70, v161, s[4:5] offset:128
	global_load_ushort v71, v161, s[4:5] offset:384
	global_load_ushort v72, v161, s[4:5] offset:640
	global_load_ushort v73, v161, s[4:5] offset:896
	global_load_ushort v74, v160, s[6:7] offset:128
	global_load_ushort v75, v160, s[6:7] offset:384
	global_load_ushort v76, v160, s[6:7] offset:640
	global_load_ushort v77, v160, s[6:7] offset:896
	global_load_ushort v78, v161, s[6:7] offset:128
	global_load_ushort v79, v161, s[6:7] offset:384
	global_load_ushort v80, v161, s[6:7] offset:640
	global_load_ushort v81, v161, s[6:7] offset:896
	s_waitcnt vmcnt(0)
	v_lshl_or_b32 v2, v66, 16, v2
	v_lshl_or_b32 v3, v67, 16, v3
	v_lshl_or_b32 v4, v68, 16, v4
	v_lshl_or_b32 v5, v69, 16, v5
	v_lshl_or_b32 v6, v70, 16, v6
	v_lshl_or_b32 v7, v71, 16, v7
	v_lshl_or_b32 v8, v72, 16, v8
	v_lshl_or_b32 v9, v73, 16, v9
	v_lshl_or_b32 v10, v74, 16, v10
	v_lshl_or_b32 v11, v75, 16, v11
	v_lshl_or_b32 v12, v76, 16, v12
	v_lshl_or_b32 v13, v77, 16, v13
	v_lshl_or_b32 v14, v78, 16, v14
	v_lshl_or_b32 v15, v79, 16, v15
	v_lshl_or_b32 v16, v80, 16, v16
	v_lshl_or_b32 v17, v81, 16, v17
	global_load_ushort v18, v160, s[4:5] offset:32
	global_load_ushort v19, v160, s[4:5] offset:288
	global_load_ushort v20, v160, s[4:5] offset:544
	global_load_ushort v21, v160, s[4:5] offset:800
	global_load_ushort v22, v161, s[4:5] offset:32
	global_load_ushort v23, v161, s[4:5] offset:288
	global_load_ushort v24, v161, s[4:5] offset:544
	global_load_ushort v25, v161, s[4:5] offset:800
	global_load_ushort v26, v160, s[6:7] offset:32
	global_load_ushort v27, v160, s[6:7] offset:288
	global_load_ushort v28, v160, s[6:7] offset:544
	global_load_ushort v29, v160, s[6:7] offset:800
	global_load_ushort v30, v161, s[6:7] offset:32
	global_load_ushort v31, v161, s[6:7] offset:288
	global_load_ushort v32, v161, s[6:7] offset:544
	global_load_ushort v33, v161, s[6:7] offset:800
	global_load_ushort v66, v160, s[4:5] offset:160
	global_load_ushort v67, v160, s[4:5] offset:416
	global_load_ushort v68, v160, s[4:5] offset:672
	global_load_ushort v69, v160, s[4:5] offset:928
	global_load_ushort v70, v161, s[4:5] offset:160
	global_load_ushort v71, v161, s[4:5] offset:416
	global_load_ushort v72, v161, s[4:5] offset:672
	global_load_ushort v73, v161, s[4:5] offset:928
	global_load_ushort v74, v160, s[6:7] offset:160
	global_load_ushort v75, v160, s[6:7] offset:416
	global_load_ushort v76, v160, s[6:7] offset:672
	global_load_ushort v77, v160, s[6:7] offset:928
	global_load_ushort v78, v161, s[6:7] offset:160
	global_load_ushort v79, v161, s[6:7] offset:416
	global_load_ushort v80, v161, s[6:7] offset:672
	global_load_ushort v81, v161, s[6:7] offset:928
	s_waitcnt vmcnt(0)
	v_lshl_or_b32 v18, v66, 16, v18
	v_lshl_or_b32 v19, v67, 16, v19
	v_lshl_or_b32 v20, v68, 16, v20
	v_lshl_or_b32 v21, v69, 16, v21
	v_lshl_or_b32 v22, v70, 16, v22
	v_lshl_or_b32 v23, v71, 16, v23
	v_lshl_or_b32 v24, v72, 16, v24
	v_lshl_or_b32 v25, v73, 16, v25
	v_lshl_or_b32 v26, v74, 16, v26
	v_lshl_or_b32 v27, v75, 16, v27
	v_lshl_or_b32 v28, v76, 16, v28
	v_lshl_or_b32 v29, v77, 16, v29
	v_lshl_or_b32 v30, v78, 16, v30
	v_lshl_or_b32 v31, v79, 16, v31
	v_lshl_or_b32 v32, v80, 16, v32
	v_lshl_or_b32 v33, v81, 16, v33
	global_load_ushort v34, v160, s[4:5] offset:64
	global_load_ushort v35, v160, s[4:5] offset:320
	global_load_ushort v36, v160, s[4:5] offset:576
	global_load_ushort v37, v160, s[4:5] offset:832
	global_load_ushort v38, v161, s[4:5] offset:64
	global_load_ushort v39, v161, s[4:5] offset:320
	global_load_ushort v40, v161, s[4:5] offset:576
	global_load_ushort v41, v161, s[4:5] offset:832
	global_load_ushort v42, v160, s[6:7] offset:64
	global_load_ushort v43, v160, s[6:7] offset:320
	global_load_ushort v44, v160, s[6:7] offset:576
	global_load_ushort v45, v160, s[6:7] offset:832
	global_load_ushort v46, v161, s[6:7] offset:64
	global_load_ushort v47, v161, s[6:7] offset:320
	global_load_ushort v48, v161, s[6:7] offset:576
	global_load_ushort v49, v161, s[6:7] offset:832
	global_load_ushort v66, v160, s[4:5] offset:192
	global_load_ushort v67, v160, s[4:5] offset:448
	global_load_ushort v68, v160, s[4:5] offset:704
	global_load_ushort v69, v160, s[4:5] offset:960
	global_load_ushort v70, v161, s[4:5] offset:192
	global_load_ushort v71, v161, s[4:5] offset:448
	global_load_ushort v72, v161, s[4:5] offset:704
	global_load_ushort v73, v161, s[4:5] offset:960
	global_load_ushort v74, v160, s[6:7] offset:192
	global_load_ushort v75, v160, s[6:7] offset:448
	global_load_ushort v76, v160, s[6:7] offset:704
	global_load_ushort v77, v160, s[6:7] offset:960
	global_load_ushort v78, v161, s[6:7] offset:192
	global_load_ushort v79, v161, s[6:7] offset:448
	global_load_ushort v80, v161, s[6:7] offset:704
	global_load_ushort v81, v161, s[6:7] offset:960
	s_waitcnt vmcnt(0)
	v_lshl_or_b32 v34, v66, 16, v34
	v_lshl_or_b32 v35, v67, 16, v35
	v_lshl_or_b32 v36, v68, 16, v36
	v_lshl_or_b32 v37, v69, 16, v37
	v_lshl_or_b32 v38, v70, 16, v38
	v_lshl_or_b32 v39, v71, 16, v39
	v_lshl_or_b32 v40, v72, 16, v40
	v_lshl_or_b32 v41, v73, 16, v41
	v_lshl_or_b32 v42, v74, 16, v42
	v_lshl_or_b32 v43, v75, 16, v43
	v_lshl_or_b32 v44, v76, 16, v44
	v_lshl_or_b32 v45, v77, 16, v45
	v_lshl_or_b32 v46, v78, 16, v46
	v_lshl_or_b32 v47, v79, 16, v47
	v_lshl_or_b32 v48, v80, 16, v48
	v_lshl_or_b32 v49, v81, 16, v49
	global_load_ushort v50, v160, s[4:5] offset:96
	global_load_ushort v51, v160, s[4:5] offset:352
	global_load_ushort v52, v160, s[4:5] offset:608
	global_load_ushort v53, v160, s[4:5] offset:864
	global_load_ushort v54, v161, s[4:5] offset:96
	global_load_ushort v55, v161, s[4:5] offset:352
	global_load_ushort v56, v161, s[4:5] offset:608
	global_load_ushort v57, v161, s[4:5] offset:864
	global_load_ushort v58, v160, s[6:7] offset:96
	global_load_ushort v59, v160, s[6:7] offset:352
	global_load_ushort v60, v160, s[6:7] offset:608
	global_load_ushort v61, v160, s[6:7] offset:864
	global_load_ushort v62, v161, s[6:7] offset:96
	global_load_ushort v63, v161, s[6:7] offset:352
	global_load_ushort v64, v161, s[6:7] offset:608
	global_load_ushort v65, v161, s[6:7] offset:864
	global_load_ushort v66, v160, s[4:5] offset:224
	global_load_ushort v67, v160, s[4:5] offset:480
	global_load_ushort v68, v160, s[4:5] offset:736
	global_load_ushort v69, v160, s[4:5] offset:992
	global_load_ushort v70, v161, s[4:5] offset:224
	global_load_ushort v71, v161, s[4:5] offset:480
	global_load_ushort v72, v161, s[4:5] offset:736
	global_load_ushort v73, v161, s[4:5] offset:992
	global_load_ushort v74, v160, s[6:7] offset:224
	global_load_ushort v75, v160, s[6:7] offset:480
	global_load_ushort v76, v160, s[6:7] offset:736
	global_load_ushort v77, v160, s[6:7] offset:992
	global_load_ushort v78, v161, s[6:7] offset:224
	global_load_ushort v79, v161, s[6:7] offset:480
	global_load_ushort v80, v161, s[6:7] offset:736
	global_load_ushort v81, v161, s[6:7] offset:992
	s_waitcnt vmcnt(0)
	v_lshl_or_b32 v50, v66, 16, v50
	v_lshl_or_b32 v51, v67, 16, v51
	v_lshl_or_b32 v52, v68, 16, v52
	v_lshl_or_b32 v53, v69, 16, v53
	v_lshl_or_b32 v54, v70, 16, v54
	v_lshl_or_b32 v55, v71, 16, v55
	v_lshl_or_b32 v56, v72, 16, v56
	v_lshl_or_b32 v57, v73, 16, v57
	v_lshl_or_b32 v58, v74, 16, v58
	v_lshl_or_b32 v59, v75, 16, v59
	v_lshl_or_b32 v60, v76, 16, v60
	v_lshl_or_b32 v61, v77, 16, v61
	v_lshl_or_b32 v62, v78, 16, v62
	v_lshl_or_b32 v63, v79, 16, v63
	v_lshl_or_b32 v64, v80, 16, v64
	v_lshl_or_b32 v65, v81, 16, v65
	s_waitcnt lgkmcnt(0)
	v_mov_b32_e32 v162, s52
	s_mov_b32 s12, 0x3b000000
	s_mov_b32 s10, 0
.Lfft_qloop:
	global_load_dwordx4 v[66:69], v145, s[8:9] offset:0
	global_load_dwordx4 v[70:73], v145, s[8:9] offset:1024
	global_load_dwordx4 v[74:77], v145, s[8:9] offset:2048
	global_load_dwordx4 v[78:81], v145, s[8:9] offset:3072
	global_load_dwordx4 v[82:85], v159, s[8:9] offset:0
	global_load_dwordx4 v[86:89], v159, s[8:9] offset:1024
	global_load_dwordx4 v[90:93], v159, s[8:9] offset:2048
	global_load_dwordx4 v[94:97], v159, s[8:9] offset:3072
	v_cvt_f32_u32_e32 v142, v141
	v_mul_f32_e32 v142, 0x39800000, v142
	v_mul_f32_e32 v143, v142, v140
	global_load_dwordx4 v[218:221], v145, s[28:29] offset:0
	global_load_dwordx4 v[222:225], v156, s[28:29] offset:0
	global_load_dwordx4 v[226:229], v157, s[28:29] offset:0
	global_load_dwordx4 v[230:233], v158, s[28:29] offset:0
	global_load_dwordx4 v[234:237], v145, s[28:29] offset:2048
	global_load_dwordx4 v[238:241], v156, s[28:29] offset:2048
	global_load_dwordx4 v[242:245], v157, s[28:29] offset:2048
	global_load_dwordx4 v[246:249], v158, s[28:29] offset:2048
	s_waitcnt vmcnt(8)
	v_mfma_f32_16x16x32_bf16 v[98:101], v[2:5], v[66:69], 0
	v_mfma_f32_16x16x32_bf16 v[102:105], v[18:21], v[66:69], 0
	v_mfma_f32_16x16x32_bf16 v[106:109], v[2:5], v[82:85], 0
	v_mfma_f32_16x16x32_bf16 v[110:113], v[18:21], v[82:85], 0
	v_mfma_f32_16x16x32_bf16 v[98:101], v[6:9], v[70:73], v[98:101]
	v_mfma_f32_16x16x32_bf16 v[102:105], v[22:25], v[70:73], v[102:105]
	v_mfma_f32_16x16x32_bf16 v[106:109], v[6:9], v[86:89], v[106:109]
	v_mfma_f32_16x16x32_bf16 v[110:113], v[22:25], v[86:89], v[110:113]
	v_mfma_f32_16x16x32_bf16 v[98:101], v[10:13], v[74:77], v[98:101]
	v_mfma_f32_16x16x32_bf16 v[102:105], v[26:29], v[74:77], v[102:105]
	v_mfma_f32_16x16x32_bf16 v[106:109], v[10:13], v[90:93], v[106:109]
	v_mfma_f32_16x16x32_bf16 v[110:113], v[26:29], v[90:93], v[110:113]
	v_mfma_f32_16x16x32_bf16 v[98:101], v[14:17], v[78:81], v[98:101]
	v_mfma_f32_16x16x32_bf16 v[102:105], v[30:33], v[78:81], v[102:105]
	v_mfma_f32_16x16x32_bf16 v[106:109], v[14:17], v[94:97], v[106:109]
	v_mfma_f32_16x16x32_bf16 v[110:113], v[30:33], v[94:97], v[110:113]
	s_nop 15
	v_fmamk_f32 v163, v142, 0x00000000, v143
	v_cos_f32_e32 v164, v163
	v_sin_f32_e32 v165, v163
	s_nop 0
	v_mul_f32_e32 v166, v164, v106
	v_mul_f32_e32 v167, v165, v106
	v_fma_f32 v106, v165, v98, v166
	v_fma_f32 v98, v164, v98, -v167
	v_fmamk_f32 v163, v142, 0x3f800000, v143
	v_cos_f32_e32 v164, v163
	v_sin_f32_e32 v165, v163
	s_nop 0
	v_mul_f32_e32 v166, v164, v107
	v_mul_f32_e32 v167, v165, v107
	v_fma_f32 v107, v165, v99, v166
	v_fma_f32 v99, v164, v99, -v167
	v_fmamk_f32 v163, v142, 0x40000000, v143
	v_cos_f32_e32 v164, v163
	v_sin_f32_e32 v165, v163
	s_nop 0
	v_mul_f32_e32 v166, v164, v108
	v_mul_f32_e32 v167, v165, v108
	v_fma_f32 v108, v165, v100, v166
	v_fma_f32 v100, v164, v100, -v167
	v_fmamk_f32 v163, v142, 0x40400000, v143
	v_cos_f32_e32 v164, v163
	v_sin_f32_e32 v165, v163
	s_nop 0
	v_mul_f32_e32 v166, v164, v109
	v_mul_f32_e32 v167, v165, v109
	v_fma_f32 v109, v165, v101, v166
	v_fma_f32 v101, v164, v101, -v167
	v_fmamk_f32 v163, v142, 0x41800000, v143
	v_cos_f32_e32 v164, v163
	v_sin_f32_e32 v165, v163
	s_nop 0
	v_mul_f32_e32 v166, v164, v110
	v_mul_f32_e32 v167, v165, v110
	v_fma_f32 v110, v165, v102, v166
	v_fma_f32 v102, v164, v102, -v167
	v_fmamk_f32 v163, v142, 0x41880000, v143
	v_cos_f32_e32 v164, v163
	v_sin_f32_e32 v165, v163
	s_nop 0
	v_mul_f32_e32 v166, v164, v111
	v_mul_f32_e32 v167, v165, v111
	v_fma_f32 v111, v165, v103, v166
	v_fma_f32 v103, v164, v103, -v167
	v_fmamk_f32 v163, v142, 0x41900000, v143
	v_cos_f32_e32 v164, v163
	v_sin_f32_e32 v165, v163
	s_nop 0
	v_mul_f32_e32 v166, v164, v112
	v_mul_f32_e32 v167, v165, v112
	v_fma_f32 v112, v165, v104, v166
	v_fma_f32 v104, v164, v104, -v167
	v_fmamk_f32 v163, v142, 0x41980000, v143
	v_cos_f32_e32 v164, v163
	v_sin_f32_e32 v165, v163
	s_nop 0
	v_mul_f32_e32 v166, v164, v113
	v_mul_f32_e32 v167, v165, v113
	v_fma_f32 v113, v165, v105, v166
	v_fma_f32 v105, v164, v105, -v167
	v_cvt_pk_bf16_f32 v114, v98, v99
	v_cvt_pk_bf16_f32 v115, v100, v101
	v_cvt_pk_bf16_f32 v116, v102, v103
	v_cvt_pk_bf16_f32 v117, v104, v105
	v_cvt_pk_bf16_f32 v118, v106, v107
	v_cvt_pk_bf16_f32 v119, v108, v109
	v_cvt_pk_bf16_f32 v120, v110, v111
	v_cvt_pk_bf16_f32 v121, v112, v113
	s_waitcnt vmcnt(0)
	s_nop 1
	v_mfma_f32_16x16x32_bf16 v[122:125], v[218:221], v[114:117], 0
	v_mfma_f32_16x16x32_bf16 v[126:129], v[222:225], v[114:117], 0
	v_mfma_f32_16x16x32_bf16 v[130:133], v[226:229], v[114:117], 0
	v_mfma_f32_16x16x32_bf16 v[134:137], v[230:233], v[114:117], 0
	v_mfma_f32_16x16x32_bf16 v[122:125], v[234:237], v[118:121], v[122:125]
	v_mfma_f32_16x16x32_bf16 v[126:129], v[238:241], v[118:121], v[126:129]
	v_mfma_f32_16x16x32_bf16 v[130:133], v[242:245], v[118:121], v[130:133]
	v_mfma_f32_16x16x32_bf16 v[134:137], v[246:249], v[118:121], v[134:137]
	global_load_dwordx4 v[218:221], v145, s[28:29] offset:1024
	global_load_dwordx4 v[222:225], v156, s[28:29] offset:1024
	global_load_dwordx4 v[226:229], v157, s[28:29] offset:1024
	global_load_dwordx4 v[230:233], v158, s[28:29] offset:1024
	global_load_dwordx4 v[234:237], v145, s[28:29] offset:3072
	global_load_dwordx4 v[238:241], v156, s[28:29] offset:3072
	global_load_dwordx4 v[242:245], v157, s[28:29] offset:3072
	global_load_dwordx4 v[246:249], v158, s[28:29] offset:3072
	v_mfma_f32_16x16x32_bf16 v[98:101], v[34:37], v[66:69], 0
	v_mfma_f32_16x16x32_bf16 v[102:105], v[50:53], v[66:69], 0
	v_mfma_f32_16x16x32_bf16 v[106:109], v[34:37], v[82:85], 0
	v_mfma_f32_16x16x32_bf16 v[110:113], v[50:53], v[82:85], 0
	v_mfma_f32_16x16x32_bf16 v[98:101], v[38:41], v[70:73], v[98:101]
	v_mfma_f32_16x16x32_bf16 v[102:105], v[54:57], v[70:73], v[102:105]
	v_mfma_f32_16x16x32_bf16 v[106:109], v[38:41], v[86:89], v[106:109]
	v_mfma_f32_16x16x32_bf16 v[110:113], v[54:57], v[86:89], v[110:113]
	v_mfma_f32_16x16x32_bf16 v[98:101], v[42:45], v[74:77], v[98:101]
	v_mfma_f32_16x16x32_bf16 v[102:105], v[58:61], v[74:77], v[102:105]
	v_mfma_f32_16x16x32_bf16 v[106:109], v[42:45], v[90:93], v[106:109]
	v_mfma_f32_16x16x32_bf16 v[110:113], v[58:61], v[90:93], v[110:113]
	v_mfma_f32_16x16x32_bf16 v[98:101], v[46:49], v[78:81], v[98:101]
	v_mfma_f32_16x16x32_bf16 v[102:105], v[62:65], v[78:81], v[102:105]
	v_mfma_f32_16x16x32_bf16 v[106:109], v[46:49], v[94:97], v[106:109]
	v_mfma_f32_16x16x32_bf16 v[110:113], v[62:65], v[94:97], v[110:113]
	s_nop 15
	v_fmamk_f32 v163, v142, 0x42000000, v143
	v_cos_f32_e32 v164, v163
	v_sin_f32_e32 v165, v163
	s_nop 0
	v_mul_f32_e32 v166, v164, v106
	v_mul_f32_e32 v167, v165, v106
	v_fma_f32 v106, v165, v98, v166
	v_fma_f32 v98, v164, v98, -v167
	v_fmamk_f32 v163, v142, 0x42040000, v143
	v_cos_f32_e32 v164, v163
	v_sin_f32_e32 v165, v163
	s_nop 0
	v_mul_f32_e32 v166, v164, v107
	v_mul_f32_e32 v167, v165, v107
	v_fma_f32 v107, v165, v99, v166
	v_fma_f32 v99, v164, v99, -v167
	v_fmamk_f32 v163, v142, 0x42080000, v143
	v_cos_f32_e32 v164, v163
	v_sin_f32_e32 v165, v163
	s_nop 0
	v_mul_f32_e32 v166, v164, v108
	v_mul_f32_e32 v167, v165, v108
	v_fma_f32 v108, v165, v100, v166
	v_fma_f32 v100, v164, v100, -v167
	v_fmamk_f32 v163, v142, 0x420c0000, v143
	v_cos_f32_e32 v164, v163
	v_sin_f32_e32 v165, v163
	s_nop 0
	v_mul_f32_e32 v166, v164, v109
	v_mul_f32_e32 v167, v165, v109
	v_fma_f32 v109, v165, v101, v166
	v_fma_f32 v101, v164, v101, -v167
	v_fmamk_f32 v163, v142, 0x42400000, v143
	v_cos_f32_e32 v164, v163
	v_sin_f32_e32 v165, v163
	s_nop 0
	v_mul_f32_e32 v166, v164, v110
	v_mul_f32_e32 v167, v165, v110
	v_fma_f32 v110, v165, v102, v166
	v_fma_f32 v102, v164, v102, -v167
	v_fmamk_f32 v163, v142, 0x42440000, v143
	v_cos_f32_e32 v164, v163
	v_sin_f32_e32 v165, v163
	s_nop 0
	v_mul_f32_e32 v166, v164, v111
	v_mul_f32_e32 v167, v165, v111
	v_fma_f32 v111, v165, v103, v166
	v_fma_f32 v103, v164, v103, -v167
	v_fmamk_f32 v163, v142, 0x42480000, v143
	v_cos_f32_e32 v164, v163
	v_sin_f32_e32 v165, v163
	s_nop 0
	v_mul_f32_e32 v166, v164, v112
	v_mul_f32_e32 v167, v165, v112
	v_fma_f32 v112, v165, v104, v166
	v_fma_f32 v104, v164, v104, -v167
	v_fmamk_f32 v163, v142, 0x424c0000, v143
	v_cos_f32_e32 v164, v163
	v_sin_f32_e32 v165, v163
	s_nop 0
	v_mul_f32_e32 v166, v164, v113
	v_mul_f32_e32 v167, v165, v113
	v_fma_f32 v113, v165, v105, v166
	v_fma_f32 v105, v164, v105, -v167
	v_cvt_pk_bf16_f32 v114, v98, v99
	v_cvt_pk_bf16_f32 v115, v100, v101
	v_cvt_pk_bf16_f32 v116, v102, v103
	v_cvt_pk_bf16_f32 v117, v104, v105
	v_cvt_pk_bf16_f32 v118, v106, v107
	v_cvt_pk_bf16_f32 v119, v108, v109
	v_cvt_pk_bf16_f32 v120, v110, v111
	v_cvt_pk_bf16_f32 v121, v112, v113
	s_waitcnt vmcnt(0)
	s_nop 1
	v_mfma_f32_16x16x32_bf16 v[122:125], v[218:221], v[114:117], v[122:125]
	v_mfma_f32_16x16x32_bf16 v[126:129], v[222:225], v[114:117], v[126:129]
	v_mfma_f32_16x16x32_bf16 v[130:133], v[226:229], v[114:117], v[130:133]
	v_mfma_f32_16x16x32_bf16 v[134:137], v[230:233], v[114:117], v[134:137]
	v_mfma_f32_16x16x32_bf16 v[122:125], v[234:237], v[118:121], v[122:125]
	v_mfma_f32_16x16x32_bf16 v[126:129], v[238:241], v[118:121], v[126:129]
	v_mfma_f32_16x16x32_bf16 v[130:133], v[242:245], v[118:121], v[130:133]
	v_mfma_f32_16x16x32_bf16 v[134:137], v[246:249], v[118:121], v[134:137]
	s_nop 15
	v_fma_f32 v166, v122, s12, v162
	v_cvt_pk_bf16_f32 v166, v166, v166
	ds_write_b16 v144, v166 offset:0
	v_fma_f32 v166, v123, s12, v162
	v_cvt_pk_bf16_f32 v166, v166, v166
	ds_write_b16 v144, v166 offset:512
	v_fma_f32 v166, v124, s12, v162
	v_cvt_pk_bf16_f32 v166, v166, v166
	ds_write_b16 v144, v166 offset:1024
	v_fma_f32 v166, v125, s12, v162
	v_cvt_pk_bf16_f32 v166, v166, v166
	ds_write_b16 v144, v166 offset:1536
	v_fma_f32 v166, v126, s12, v162
	v_cvt_pk_bf16_f32 v166, v166, v166
	ds_write_b16 v144, v166 offset:8192
	v_fma_f32 v166, v127, s12, v162
	v_cvt_pk_bf16_f32 v166, v166, v166
	ds_write_b16 v144, v166 offset:8704
	v_fma_f32 v166, v128, s12, v162
	v_cvt_pk_bf16_f32 v166, v166, v166
	ds_write_b16 v144, v166 offset:9216
	v_fma_f32 v166, v129, s12, v162
	v_cvt_pk_bf16_f32 v166, v166, v166
	ds_write_b16 v144, v166 offset:9728
	v_fma_f32 v166, v130, s12, v162
	v_cvt_pk_bf16_f32 v166, v166, v166
	ds_write_b16 v144, v166 offset:16384
	v_fma_f32 v166, v131, s12, v162
	v_cvt_pk_bf16_f32 v166, v166, v166
	ds_write_b16 v144, v166 offset:16896
	v_fma_f32 v166, v132, s12, v162
	v_cvt_pk_bf16_f32 v166, v166, v166
	ds_write_b16 v144, v166 offset:17408
	v_fma_f32 v166, v133, s12, v162
	v_cvt_pk_bf16_f32 v166, v166, v166
	ds_write_b16 v144, v166 offset:17920
	v_fma_f32 v166, v134, s12, v162
	v_cvt_pk_bf16_f32 v166, v166, v166
	ds_write_b16 v144, v166 offset:24576
	v_fma_f32 v166, v135, s12, v162
	v_cvt_pk_bf16_f32 v166, v166, v166
	ds_write_b16 v144, v166 offset:25088
	v_fma_f32 v166, v136, s12, v162
	v_cvt_pk_bf16_f32 v166, v166, v166
	ds_write_b16 v144, v166 offset:25600
	v_fma_f32 v166, v137, s12, v162
	v_cvt_pk_bf16_f32 v166, v166, v166
	ds_write_b16 v144, v166 offset:26112
	v_add_u32_e32 v141, 16, v141
	v_add_u32_e32 v144, 0x80, v144
	s_add_u32 s8, s8, 0x1000
	s_addc_u32 s9, s9, 0
	s_add_i32 s10, s10, 1
	s_cmp_lt_u32 s10, 4
	s_cbranch_scc1 .Lfft_qloop
	s_waitcnt lgkmcnt(0)
	s_barrier
	v_lshlrev_b32_e32 v168, 3, v151
	v_mul_u32_u24_e32 v169, 0x600, v151
	v_lshlrev_b32_e32 v170, 11, v151
	ds_read_b64 v[2:3], v168 offset:0
	global_load_dwordx2 v[4:5], v169, s[38:39]
	v_add_u32_e32 v169, 0x60000, v169
	ds_read_b64 v[10:11], v168 offset:2048
	global_load_dwordx2 v[12:13], v169, s[38:39]
	v_add_u32_e32 v169, 0x60000, v169
	ds_read_b64 v[18:19], v168 offset:4096
	global_load_dwordx2 v[20:21], v169, s[38:39]
	v_add_u32_e32 v169, 0x60000, v169
	ds_read_b64 v[26:27], v168 offset:6144
	global_load_dwordx2 v[28:29], v169, s[38:39]
	v_add_u32_e32 v169, 0x60000, v169
	ds_read_b64 v[34:35], v168 offset:8192
	global_load_dwordx2 v[36:37], v169, s[38:39]
	v_add_u32_e32 v169, 0x60000, v169
	ds_read_b64 v[42:43], v168 offset:10240
	global_load_dwordx2 v[44:45], v169, s[38:39]
	v_add_u32_e32 v169, 0x60000, v169
	ds_read_b64 v[50:51], v168 offset:12288
	global_load_dwordx2 v[52:53], v169, s[38:39]
	v_add_u32_e32 v169, 0x60000, v169
	ds_read_b64 v[58:59], v168 offset:14336
	global_load_dwordx2 v[60:61], v169, s[38:39]
	v_add_u32_e32 v169, 0x60000, v169
	ds_read_b64 v[66:67], v168 offset:16384
	global_load_dwordx2 v[68:69], v169, s[38:39]
	v_add_u32_e32 v169, 0x60000, v169
	ds_read_b64 v[74:75], v168 offset:18432
	global_load_dwordx2 v[76:77], v169, s[38:39]
	v_add_u32_e32 v169, 0x60000, v169
	ds_read_b64 v[82:83], v168 offset:20480
	global_load_dwordx2 v[84:85], v169, s[38:39]
	v_add_u32_e32 v169, 0x60000, v169
	ds_read_b64 v[90:91], v168 offset:22528
	global_load_dwordx2 v[92:93], v169, s[38:39]
	v_add_u32_e32 v169, 0x60000, v169
	ds_read_b64 v[98:99], v168 offset:24576
	global_load_dwordx2 v[100:101], v169, s[38:39]
	v_add_u32_e32 v169, 0x60000, v169
	ds_read_b64 v[106:107], v168 offset:26624
	global_load_dwordx2 v[108:109], v169, s[38:39]
	v_add_u32_e32 v169, 0x60000, v169
	ds_read_b64 v[114:115], v168 offset:28672
	global_load_dwordx2 v[116:117], v169, s[38:39]
	v_add_u32_e32 v169, 0x60000, v169
	ds_read_b64 v[122:123], v168 offset:30720
	global_load_dwordx2 v[124:125], v169, s[38:39]
	s_waitcnt vmcnt(15) lgkmcnt(15)
	v_lshlrev_b32_e32 v6, 16, v2
	v_and_b32_e32 v7, 0xffff0000, v2
	v_lshlrev_b32_e32 v8, 16, v4
	v_and_b32_e32 v9, 0xffff0000, v4
	v_mul_f32_e32 v6, v6, v8
	v_mul_f32_e32 v7, v7, v9
	v_cvt_pk_bf16_f32 v2, v6, v7
	v_lshlrev_b32_e32 v6, 16, v3
	v_and_b32_e32 v7, 0xffff0000, v3
	v_lshlrev_b32_e32 v8, 16, v5
	v_and_b32_e32 v9, 0xffff0000, v5
	v_mul_f32_e32 v6, v6, v8
	v_mul_f32_e32 v7, v7, v9
	v_cvt_pk_bf16_f32 v3, v6, v7
	global_store_dwordx2 v170, v[2:3], s[40:41]
	v_add_u32_e32 v170, 0x80000, v170
	s_waitcnt vmcnt(15) lgkmcnt(14)
	v_lshlrev_b32_e32 v14, 16, v10
	v_and_b32_e32 v15, 0xffff0000, v10
	v_lshlrev_b32_e32 v16, 16, v12
	v_and_b32_e32 v17, 0xffff0000, v12
	v_mul_f32_e32 v14, v14, v16
	v_mul_f32_e32 v15, v15, v17
	v_cvt_pk_bf16_f32 v10, v14, v15
	v_lshlrev_b32_e32 v14, 16, v11
	v_and_b32_e32 v15, 0xffff0000, v11
	v_lshlrev_b32_e32 v16, 16, v13
	v_and_b32_e32 v17, 0xffff0000, v13
	v_mul_f32_e32 v14, v14, v16
	v_mul_f32_e32 v15, v15, v17
	v_cvt_pk_bf16_f32 v11, v14, v15
	global_store_dwordx2 v170, v[10:11], s[40:41]
	v_add_u32_e32 v170, 0x80000, v170
	s_waitcnt vmcnt(15) lgkmcnt(13)
	v_lshlrev_b32_e32 v22, 16, v18
	v_and_b32_e32 v23, 0xffff0000, v18
	v_lshlrev_b32_e32 v24, 16, v20
	v_and_b32_e32 v25, 0xffff0000, v20
	v_mul_f32_e32 v22, v22, v24
	v_mul_f32_e32 v23, v23, v25
	v_cvt_pk_bf16_f32 v18, v22, v23
	v_lshlrev_b32_e32 v22, 16, v19
	v_and_b32_e32 v23, 0xffff0000, v19
	v_lshlrev_b32_e32 v24, 16, v21
	v_and_b32_e32 v25, 0xffff0000, v21
	v_mul_f32_e32 v22, v22, v24
	v_mul_f32_e32 v23, v23, v25
	v_cvt_pk_bf16_f32 v19, v22, v23
	global_store_dwordx2 v170, v[18:19], s[40:41]
	v_add_u32_e32 v170, 0x80000, v170
	s_waitcnt vmcnt(15) lgkmcnt(12)
	v_lshlrev_b32_e32 v30, 16, v26
	v_and_b32_e32 v31, 0xffff0000, v26
	v_lshlrev_b32_e32 v32, 16, v28
	v_and_b32_e32 v33, 0xffff0000, v28
	v_mul_f32_e32 v30, v30, v32
	v_mul_f32_e32 v31, v31, v33
	v_cvt_pk_bf16_f32 v26, v30, v31
	v_lshlrev_b32_e32 v30, 16, v27
	v_and_b32_e32 v31, 0xffff0000, v27
	v_lshlrev_b32_e32 v32, 16, v29
	v_and_b32_e32 v33, 0xffff0000, v29
	v_mul_f32_e32 v30, v30, v32
	v_mul_f32_e32 v31, v31, v33
	v_cvt_pk_bf16_f32 v27, v30, v31
	global_store_dwordx2 v170, v[26:27], s[40:41]
	v_add_u32_e32 v170, 0x80000, v170
	s_waitcnt vmcnt(15) lgkmcnt(11)
	v_lshlrev_b32_e32 v38, 16, v34
	v_and_b32_e32 v39, 0xffff0000, v34
	v_lshlrev_b32_e32 v40, 16, v36
	v_and_b32_e32 v41, 0xffff0000, v36
	v_mul_f32_e32 v38, v38, v40
	v_mul_f32_e32 v39, v39, v41
	v_cvt_pk_bf16_f32 v34, v38, v39
	v_lshlrev_b32_e32 v38, 16, v35
	v_and_b32_e32 v39, 0xffff0000, v35
	v_lshlrev_b32_e32 v40, 16, v37
	v_and_b32_e32 v41, 0xffff0000, v37
	v_mul_f32_e32 v38, v38, v40
	v_mul_f32_e32 v39, v39, v41
	v_cvt_pk_bf16_f32 v35, v38, v39
	global_store_dwordx2 v170, v[34:35], s[40:41]
	v_add_u32_e32 v170, 0x80000, v170
	s_waitcnt vmcnt(15) lgkmcnt(10)
	v_lshlrev_b32_e32 v46, 16, v42
	v_and_b32_e32 v47, 0xffff0000, v42
	v_lshlrev_b32_e32 v48, 16, v44
	v_and_b32_e32 v49, 0xffff0000, v44
	v_mul_f32_e32 v46, v46, v48
	v_mul_f32_e32 v47, v47, v49
	v_cvt_pk_bf16_f32 v42, v46, v47
	v_lshlrev_b32_e32 v46, 16, v43
	v_and_b32_e32 v47, 0xffff0000, v43
	v_lshlrev_b32_e32 v48, 16, v45
	v_and_b32_e32 v49, 0xffff0000, v45
	v_mul_f32_e32 v46, v46, v48
	v_mul_f32_e32 v47, v47, v49
	v_cvt_pk_bf16_f32 v43, v46, v47
	global_store_dwordx2 v170, v[42:43], s[40:41]
	v_add_u32_e32 v170, 0x80000, v170
	s_waitcnt vmcnt(15) lgkmcnt(9)
	v_lshlrev_b32_e32 v54, 16, v50
	v_and_b32_e32 v55, 0xffff0000, v50
	v_lshlrev_b32_e32 v56, 16, v52
	v_and_b32_e32 v57, 0xffff0000, v52
	v_mul_f32_e32 v54, v54, v56
	v_mul_f32_e32 v55, v55, v57
	v_cvt_pk_bf16_f32 v50, v54, v55
	v_lshlrev_b32_e32 v54, 16, v51
	v_and_b32_e32 v55, 0xffff0000, v51
	v_lshlrev_b32_e32 v56, 16, v53
	v_and_b32_e32 v57, 0xffff0000, v53
	v_mul_f32_e32 v54, v54, v56
	v_mul_f32_e32 v55, v55, v57
	v_cvt_pk_bf16_f32 v51, v54, v55
	global_store_dwordx2 v170, v[50:51], s[40:41]
	v_add_u32_e32 v170, 0x80000, v170
	s_waitcnt vmcnt(15) lgkmcnt(8)
	v_lshlrev_b32_e32 v62, 16, v58
	v_and_b32_e32 v63, 0xffff0000, v58
	v_lshlrev_b32_e32 v64, 16, v60
	v_and_b32_e32 v65, 0xffff0000, v60
	v_mul_f32_e32 v62, v62, v64
	v_mul_f32_e32 v63, v63, v65
	v_cvt_pk_bf16_f32 v58, v62, v63
	v_lshlrev_b32_e32 v62, 16, v59
	v_and_b32_e32 v63, 0xffff0000, v59
	v_lshlrev_b32_e32 v64, 16, v61
	v_and_b32_e32 v65, 0xffff0000, v61
	v_mul_f32_e32 v62, v62, v64
	v_mul_f32_e32 v63, v63, v65
	v_cvt_pk_bf16_f32 v59, v62, v63
	global_store_dwordx2 v170, v[58:59], s[40:41]
	v_add_u32_e32 v170, 0x80000, v170
	s_waitcnt vmcnt(15) lgkmcnt(7)
	v_lshlrev_b32_e32 v70, 16, v66
	v_and_b32_e32 v71, 0xffff0000, v66
	v_lshlrev_b32_e32 v72, 16, v68
	v_and_b32_e32 v73, 0xffff0000, v68
	v_mul_f32_e32 v70, v70, v72
	v_mul_f32_e32 v71, v71, v73
	v_cvt_pk_bf16_f32 v66, v70, v71
	v_lshlrev_b32_e32 v70, 16, v67
	v_and_b32_e32 v71, 0xffff0000, v67
	v_lshlrev_b32_e32 v72, 16, v69
	v_and_b32_e32 v73, 0xffff0000, v69
	v_mul_f32_e32 v70, v70, v72
	v_mul_f32_e32 v71, v71, v73
	v_cvt_pk_bf16_f32 v67, v70, v71
	global_store_dwordx2 v170, v[66:67], s[40:41]
	v_add_u32_e32 v170, 0x80000, v170
	s_waitcnt vmcnt(15) lgkmcnt(6)
	v_lshlrev_b32_e32 v78, 16, v74
	v_and_b32_e32 v79, 0xffff0000, v74
	v_lshlrev_b32_e32 v80, 16, v76
	v_and_b32_e32 v81, 0xffff0000, v76
	v_mul_f32_e32 v78, v78, v80
	v_mul_f32_e32 v79, v79, v81
	v_cvt_pk_bf16_f32 v74, v78, v79
	v_lshlrev_b32_e32 v78, 16, v75
	v_and_b32_e32 v79, 0xffff0000, v75
	v_lshlrev_b32_e32 v80, 16, v77
	v_and_b32_e32 v81, 0xffff0000, v77
	v_mul_f32_e32 v78, v78, v80
	v_mul_f32_e32 v79, v79, v81
	v_cvt_pk_bf16_f32 v75, v78, v79
	global_store_dwordx2 v170, v[74:75], s[40:41]
	v_add_u32_e32 v170, 0x80000, v170
	s_waitcnt vmcnt(15) lgkmcnt(5)
	v_lshlrev_b32_e32 v86, 16, v82
	v_and_b32_e32 v87, 0xffff0000, v82
	v_lshlrev_b32_e32 v88, 16, v84
	v_and_b32_e32 v89, 0xffff0000, v84
	v_mul_f32_e32 v86, v86, v88
	v_mul_f32_e32 v87, v87, v89
	v_cvt_pk_bf16_f32 v82, v86, v87
	v_lshlrev_b32_e32 v86, 16, v83
	v_and_b32_e32 v87, 0xffff0000, v83
	v_lshlrev_b32_e32 v88, 16, v85
	v_and_b32_e32 v89, 0xffff0000, v85
	v_mul_f32_e32 v86, v86, v88
	v_mul_f32_e32 v87, v87, v89
	v_cvt_pk_bf16_f32 v83, v86, v87
	global_store_dwordx2 v170, v[82:83], s[40:41]
	v_add_u32_e32 v170, 0x80000, v170
	s_waitcnt vmcnt(15) lgkmcnt(4)
	v_lshlrev_b32_e32 v94, 16, v90
	v_and_b32_e32 v95, 0xffff0000, v90
	v_lshlrev_b32_e32 v96, 16, v92
	v_and_b32_e32 v97, 0xffff0000, v92
	v_mul_f32_e32 v94, v94, v96
	v_mul_f32_e32 v95, v95, v97
	v_cvt_pk_bf16_f32 v90, v94, v95
	v_lshlrev_b32_e32 v94, 16, v91
	v_and_b32_e32 v95, 0xffff0000, v91
	v_lshlrev_b32_e32 v96, 16, v93
	v_and_b32_e32 v97, 0xffff0000, v93
	v_mul_f32_e32 v94, v94, v96
	v_mul_f32_e32 v95, v95, v97
	v_cvt_pk_bf16_f32 v91, v94, v95
	global_store_dwordx2 v170, v[90:91], s[40:41]
	v_add_u32_e32 v170, 0x80000, v170
	s_waitcnt vmcnt(15) lgkmcnt(3)
	v_lshlrev_b32_e32 v102, 16, v98
	v_and_b32_e32 v103, 0xffff0000, v98
	v_lshlrev_b32_e32 v104, 16, v100
	v_and_b32_e32 v105, 0xffff0000, v100
	v_mul_f32_e32 v102, v102, v104
	v_mul_f32_e32 v103, v103, v105
	v_cvt_pk_bf16_f32 v98, v102, v103
	v_lshlrev_b32_e32 v102, 16, v99
	v_and_b32_e32 v103, 0xffff0000, v99
	v_lshlrev_b32_e32 v104, 16, v101
	v_and_b32_e32 v105, 0xffff0000, v101
	v_mul_f32_e32 v102, v102, v104
	v_mul_f32_e32 v103, v103, v105
	v_cvt_pk_bf16_f32 v99, v102, v103
	global_store_dwordx2 v170, v[98:99], s[40:41]
	v_add_u32_e32 v170, 0x80000, v170
	s_waitcnt vmcnt(15) lgkmcnt(2)
	v_lshlrev_b32_e32 v110, 16, v106
	v_and_b32_e32 v111, 0xffff0000, v106
	v_lshlrev_b32_e32 v112, 16, v108
	v_and_b32_e32 v113, 0xffff0000, v108
	v_mul_f32_e32 v110, v110, v112
	v_mul_f32_e32 v111, v111, v113
	v_cvt_pk_bf16_f32 v106, v110, v111
	v_lshlrev_b32_e32 v110, 16, v107
	v_and_b32_e32 v111, 0xffff0000, v107
	v_lshlrev_b32_e32 v112, 16, v109
	v_and_b32_e32 v113, 0xffff0000, v109
	v_mul_f32_e32 v110, v110, v112
	v_mul_f32_e32 v111, v111, v113
	v_cvt_pk_bf16_f32 v107, v110, v111
	global_store_dwordx2 v170, v[106:107], s[40:41]
	v_add_u32_e32 v170, 0x80000, v170
	s_waitcnt vmcnt(15) lgkmcnt(1)
	v_lshlrev_b32_e32 v118, 16, v114
	v_and_b32_e32 v119, 0xffff0000, v114
	v_lshlrev_b32_e32 v120, 16, v116
	v_and_b32_e32 v121, 0xffff0000, v116
	v_mul_f32_e32 v118, v118, v120
	v_mul_f32_e32 v119, v119, v121
	v_cvt_pk_bf16_f32 v114, v118, v119
	v_lshlrev_b32_e32 v118, 16, v115
	v_and_b32_e32 v119, 0xffff0000, v115
	v_lshlrev_b32_e32 v120, 16, v117
	v_and_b32_e32 v121, 0xffff0000, v117
	v_mul_f32_e32 v118, v118, v120
	v_mul_f32_e32 v119, v119, v121
	v_cvt_pk_bf16_f32 v115, v118, v119
	global_store_dwordx2 v170, v[114:115], s[40:41]
	v_add_u32_e32 v170, 0x80000, v170
	s_waitcnt vmcnt(15) lgkmcnt(0)
	v_lshlrev_b32_e32 v126, 16, v122
	v_and_b32_e32 v127, 0xffff0000, v122
	v_lshlrev_b32_e32 v128, 16, v124
	v_and_b32_e32 v129, 0xffff0000, v124
	v_mul_f32_e32 v126, v126, v128
	v_mul_f32_e32 v127, v127, v129
	v_cvt_pk_bf16_f32 v122, v126, v127
	v_lshlrev_b32_e32 v126, 16, v123
	v_and_b32_e32 v127, 0xffff0000, v123
	v_lshlrev_b32_e32 v128, 16, v125
	v_and_b32_e32 v129, 0xffff0000, v125
	v_mul_f32_e32 v126, v126, v128
	v_mul_f32_e32 v127, v127, v129
	v_cvt_pk_bf16_f32 v123, v126, v127
	global_store_dwordx2 v170, v[122:123], s[40:41]

.LBB0_744:
	v_readlane_b32 s7, v252, 0
	s_nop 3
	s_cmp_gt_u32 s7, 47
	s_cbranch_scc1 .Lfft_tab_done
	v_lshrrev_b32_e32 v2, 2, v151
	v_and_b32_e32 v3, 3, v151
	v_and_b32_e32 v4, 15, v2
	v_lshrrev_b32_e32 v5, 4, v2
	s_cmp_gt_u32 s7, 31
	s_cbranch_scc1 .Lfft_tab_t2
	s_lshr_b32 s0, s7, 2
	s_and_b32 s1, s7, 3
	s_and_b32 s4, s0, 3
	s_lshl_b32 s4, s4, 4
	v_add_u32_e32 v6, s4, v4
	s_and_b32 s4, s1, 1
	s_lshl_b32 s4, s4, 5
	v_lshl_add_u32 v7, v5, 3, s4
	v_lshl_add_u32 v7, v3, 1, v7
	s_lshr_b32 s4, s1, 1
	s_lshr_b32 s5, s0, 2
	s_sub_i32 s4, s4, s5
	v_cvt_f32_i32_e32 v8, s4
	v_mul_f32_e32 v8, 0x3e800000, v8
	v_mul_u32_u24_e32 v9, v6, v7
	v_add_u32_e32 v10, v9, v6
	s_add_u32 s4, s94, 0xfca0000
	s_addc_u32 s5, s95, 0
	s_branch .Lfft_tab_common
.Lfft_tab_t2:
	s_add_i32 s0, s7, 0xffffffe0
	s_lshr_b32 s1, s0, 2
	s_and_b32 s0, s0, 3
	s_lshl_b32 s1, s1, 4
	v_add_u32_e32 v6, s1, v4
	s_and_b32 s1, s0, 1
	s_lshl_b32 s1, s1, 5
	v_lshl_add_u32 v7, v5, 2, s1
	v_lshrrev_b32_e32 v8, 1, v3
	v_lshl_add_u32 v7, v8, 4, v7
	v_and_b32_e32 v8, 1, v3
	v_lshl_add_u32 v7, v8, 1, v7
	s_lshr_b32 s0, s0, 1
	v_cvt_f32_i32_e32 v8, s0
	v_mul_f32_e32 v8, 0x3e800000, v8
	v_mul_u32_u24_e32 v9, v6, v7
	v_add_u32_e32 v10, v9, v6
	s_add_u32 s4, s94, 0xfca8000
	s_addc_u32 s5, s95, 0
	s_add_i32 s7, s7, 0xffffffe0
.Lfft_tab_common:
	v_and_b32_e32 v9, 63, v9
	v_and_b32_e32 v10, 63, v10
	v_cvt_f32_u32_e32 v9, v9
	v_cvt_f32_u32_e32 v10, v10
	v_fmamk_f32 v9, v9, 0x3c800000, v8
	v_fmamk_f32 v10, v10, 0x3c800000, v8
	v_cos_f32_e32 v9, v9
	v_cos_f32_e32 v10, v10
	s_nop 0
	v_cvt_pk_bf16_f32 v9, v9, v10
	s_lshl_b32 s0, s7, 10
	v_lshl_add_u32 v11, v151, 2, s0
	global_store_dword v11, v9, s[4:5]
